# as v49 with the SSD S^T / Y^T operand reads issued three MFMAs ahead (five rotating operand sets)
# baseline (speedup 1.0000x reference)
.LBB0_2435:
	s_cmp_lt_u32 s38, 6
	s_cselect_b32 s39, 2, 3
	s_cmp_gt_u32 s38, 2
	s_cselect_b32 s39, s39, 1
	s_cmp_gt_i32 s38, 0
	s_cselect_b32 s39, s39, 0
	s_add_i32 s62, s39, 1
	s_mul_i32 s62, s62, s39
	s_lshr_b32 s62, s62, 1
	s_mul_i32 s63, s62, 0xffffde00
	s_add_i32 s63, s63, 0
	v_lshl_or_b32 v110, s39, 5, v74
	v_add_u32_e32 v111, s63, v98
	v_mad_u32_u24 v112, v110, s55, v97
	ds_read_b128 v[120:123], v111
	ds_read_b128 v[128:131], v111 offset:32
	ds_read_b128 v[124:127], v112
	ds_read_b128 v[132:135], v112 offset:32
	s_lshl_b32 s63, s62, 5
	s_lshl_b32 s39, s39, 6
	v_add_u32_e32 v98, 0x11000, v98
	ds_read_b128 v[136:139], v111 offset:64
	ds_read_b128 v[140:143], v112 offset:64
	ds_read_b128 v[144:147], v111 offset:96
	ds_read_b128 v[148:151], v112 offset:96
	s_waitcnt lgkmcnt(5)
	v_mfma_f32_32x32x16_bf16 v[18:33], v[120:123], v[124:127], 0
	ds_read_b128 v[152:155], v111 offset:128
	ds_read_b128 v[156:159], v112 offset:128
	s_waitcnt lgkmcnt(6)
	v_mfma_f32_32x32x16_bf16 v[18:33], v[128:131], v[132:135], v[18:33]
	ds_read_b128 v[120:123], v111 offset:160
	ds_read_b128 v[124:127], v112 offset:160
	s_waitcnt lgkmcnt(6)
	v_mfma_f32_32x32x16_bf16 v[18:33], v[136:139], v[140:143], v[18:33]
	ds_read_b128 v[128:131], v111 offset:192
	ds_read_b128 v[132:135], v112 offset:192
	s_waitcnt lgkmcnt(6)
	v_mfma_f32_32x32x16_bf16 v[18:33], v[144:147], v[148:151], v[18:33]
	ds_read_b128 v[136:139], v111 offset:224
	ds_read_b128 v[140:143], v112 offset:224
	s_waitcnt lgkmcnt(6)
	v_mfma_f32_32x32x16_bf16 v[18:33], v[152:155], v[156:159], v[18:33]
	s_waitcnt lgkmcnt(4)
	v_mfma_f32_32x32x16_bf16 v[18:33], v[120:123], v[124:127], v[18:33]
	s_waitcnt lgkmcnt(2)
	v_mfma_f32_32x32x16_bf16 v[18:33], v[128:131], v[132:135], v[18:33]
	s_waitcnt lgkmcnt(0)
	v_mfma_f32_32x32x16_bf16 v[18:33], v[136:139], v[140:143], v[18:33]
	v_subrev_u32_e32 v112, s63, v100
	s_lshl_b32 s63, s62, 7
	s_sub_i32 s63, 0, s63
	v_add_u32_e32 v114, s63, v99
	s_mulk_i32 s62, 0x2200
	v_subrev_u32_e32 v113, 27, v112
	v_lshl_add_u32 v102, v110, 2, 0
	v_add_u32_e32 v102, 0x27000, v102
	v_add_u32_e32 v106, 0x27200, v114
	ds_read_b32 v111, v102
	ds_read_b128 v[106:109], v106
	v_add_u32_e32 v102, 0x27000, v114
	ds_read_b128 v[102:105], v102
	s_sub_i32 s39, s39, s62
	v_cmp_le_i32_e32 vcc, v113, v110
	s_add_i32 s39, s39, 0
	v_add_u32_e32 v99, 0x400, v99
	s_waitcnt lgkmcnt(0)
	v_sub_f32_e32 v102, v111, v102
	v_mul_f32_e32 v102, 0x3fb8aa3b, v102
	v_exp_f32_e32 v102, v102
	v_add_u32_e32 v100, 0x100, v100
	v_mul_f32_e32 v18, v18, v102
	v_mul_f32_e32 v18, v106, v18
	v_cndmask_b32_e32 v18, 0, v18, vcc
	v_add_u32_e32 v106, s39, v101
	v_cvt_pk_bf16_f32 v18, v18, v75
	v_add_u32_e32 v102, 0x1a000, v106
	ds_write_b16 v102, v18
	v_sub_f32_e32 v18, v111, v103
	v_mul_f32_e32 v18, 0x3fb8aa3b, v18
	v_exp_f32_e32 v18, v18
	v_cmp_lt_i32_e32 vcc, v113, v110
	v_add_u32_e32 v102, 0x27220, v114
	s_add_i32 s39, s38, 8
	v_mul_f32_e32 v18, v19, v18
	v_mul_f32_e32 v18, v107, v18
	v_cndmask_b32_e32 v18, 0, v18, vcc
	v_add_u32_e32 v19, 0x1a110, v106
	v_cvt_pk_bf16_f32 v18, v18, v75
	ds_write_b16 v19, v18
	v_sub_f32_e32 v19, v111, v104
	v_mul_f32_e32 v19, 0x3fb8aa3b, v19
	v_exp_f32_e32 v19, v19
	v_subrev_u32_e32 v18, 25, v112
	v_cmp_le_i32_e32 vcc, v18, v110
	v_subrev_u32_e32 v107, 19, v112
	v_mul_f32_e32 v19, v20, v19
	v_mul_f32_e32 v19, v108, v19
	v_cndmask_b32_e32 v18, 0, v19, vcc
	v_add_u32_e32 v19, 0x1a220, v106
	v_cvt_pk_bf16_f32 v18, v18, v75
	ds_write_b16 v19, v18
	v_sub_f32_e32 v19, v111, v105
	v_mul_f32_e32 v19, 0x3fb8aa3b, v19
	v_exp_f32_e32 v19, v19
	v_subrev_u32_e32 v18, 24, v112
	v_cmp_le_i32_e32 vcc, v18, v110
	v_add_u32_e32 v101, 0x11000, v101
	v_mul_f32_e32 v19, v21, v19
	v_mul_f32_e32 v19, v109, v19
	v_cndmask_b32_e32 v18, 0, v19, vcc
	v_cvt_pk_bf16_f32 v18, v18, v75
	v_add_u32_e32 v19, 0x1a330, v106
	ds_write_b16 v19, v18
	v_add_u32_e32 v18, 0x27020, v114
	ds_read_b128 v[18:21], v18
	ds_read_b128 v[102:105], v102
	v_cmp_le_i32_e32 vcc, v107, v110
	s_cmp_gt_i32 s38, 1
	s_mov_b32 s38, s39
	s_waitcnt lgkmcnt(1)
	v_sub_f32_e32 v18, v111, v18
	v_mul_f32_e32 v18, 0x3fb8aa3b, v18
	v_exp_f32_e32 v18, v18
	s_nop 0
	v_mul_f32_e32 v18, v22, v18
	s_waitcnt lgkmcnt(0)
	v_mul_f32_e32 v18, v102, v18
	v_cndmask_b32_e32 v18, 0, v18, vcc
	v_cvt_pk_bf16_f32 v18, v18, v75
	v_add_u32_e32 v22, 0x1a880, v106
	ds_write_b16 v22, v18
	v_sub_f32_e32 v18, v111, v19
	v_mul_f32_e32 v18, 0x3fb8aa3b, v18
	v_exp_f32_e32 v18, v18
	v_cmp_lt_i32_e32 vcc, v107, v110
	v_add_u32_e32 v19, 0x1a990, v106
	v_add_u32_e32 v22, 0x27240, v114
	v_mul_f32_e32 v18, v23, v18
	v_mul_f32_e32 v18, v103, v18
	v_cndmask_b32_e32 v18, 0, v18, vcc
	v_cvt_pk_bf16_f32 v18, v18, v75
	ds_write_b16 v19, v18
	v_sub_f32_e32 v19, v111, v20
	v_mul_f32_e32 v19, 0x3fb8aa3b, v19
	v_exp_f32_e32 v19, v19
	v_subrev_u32_e32 v18, 17, v112
	v_cmp_le_i32_e32 vcc, v18, v110
	v_add_u32_e32 v102, -11, v112
	v_mul_f32_e32 v19, v24, v19
	v_mul_f32_e32 v19, v104, v19
	v_cndmask_b32_e32 v18, 0, v19, vcc
	v_add_u32_e32 v19, 0x1aaa0, v106
	v_cvt_pk_bf16_f32 v18, v18, v75
	ds_write_b16 v19, v18
	v_sub_f32_e32 v19, v111, v21
	v_mul_f32_e32 v19, 0x3fb8aa3b, v19
	v_exp_f32_e32 v19, v19
	v_add_u32_e32 v18, -16, v112
	v_cmp_le_i32_e32 vcc, v18, v110
	v_mul_f32_e32 v19, v25, v19
	v_mul_f32_e32 v19, v105, v19
	v_cndmask_b32_e32 v18, 0, v19, vcc
	v_cvt_pk_bf16_f32 v18, v18, v75
	v_add_u32_e32 v19, 0x1abb0, v106
	ds_write_b16 v19, v18
	v_add_u32_e32 v18, 0x27040, v114
	ds_read_b128 v[18:21], v18
	ds_read_b128 v[22:25], v22
	v_cmp_le_i32_e32 vcc, v102, v110
	s_waitcnt lgkmcnt(1)
	v_sub_f32_e32 v18, v111, v18
	v_mul_f32_e32 v18, 0x3fb8aa3b, v18
	v_exp_f32_e32 v18, v18
	s_nop 0
	v_mul_f32_e32 v18, v26, v18
	s_waitcnt lgkmcnt(0)
	v_mul_f32_e32 v18, v22, v18
	v_cndmask_b32_e32 v18, 0, v18, vcc
	v_cvt_pk_bf16_f32 v18, v18, v75
	v_add_u32_e32 v22, 0x1b100, v106
	ds_write_b16 v22, v18
	v_sub_f32_e32 v18, v111, v19
	v_mul_f32_e32 v18, 0x3fb8aa3b, v18
	v_exp_f32_e32 v18, v18
	v_cmp_lt_i32_e32 vcc, v102, v110
	v_add_u32_e32 v19, 0x1b210, v106
	v_add_u32_e32 v22, 0x27260, v114
	v_mul_f32_e32 v18, v27, v18
	v_mul_f32_e32 v18, v23, v18
	v_cndmask_b32_e32 v18, 0, v18, vcc
	v_cvt_pk_bf16_f32 v18, v18, v75
	ds_write_b16 v19, v18
	v_sub_f32_e32 v19, v111, v20
	v_mul_f32_e32 v19, 0x3fb8aa3b, v19
	v_exp_f32_e32 v19, v19
	v_add_u32_e32 v18, -9, v112
	v_cmp_le_i32_e32 vcc, v18, v110
	v_add_u32_e32 v26, -3, v112
	v_mul_f32_e32 v19, v28, v19
	v_mul_f32_e32 v19, v24, v19
	v_cndmask_b32_e32 v18, 0, v19, vcc
	v_add_u32_e32 v19, 0x1b320, v106
	v_cvt_pk_bf16_f32 v18, v18, v75
	ds_write_b16 v19, v18
	v_sub_f32_e32 v19, v111, v21
	v_mul_f32_e32 v19, 0x3fb8aa3b, v19
	v_exp_f32_e32 v19, v19
	v_add_u32_e32 v18, -8, v112
	v_cmp_le_i32_e32 vcc, v18, v110
	v_mul_f32_e32 v19, v29, v19
	v_mul_f32_e32 v19, v25, v19
	v_cndmask_b32_e32 v18, 0, v19, vcc
	v_cvt_pk_bf16_f32 v18, v18, v75
	v_add_u32_e32 v19, 0x1b430, v106
	ds_write_b16 v19, v18
	v_add_u32_e32 v18, 0x27060, v114
	ds_read_b128 v[18:21], v18
	ds_read_b128 v[22:25], v22
	v_cmp_le_i32_e32 vcc, v26, v110
	s_waitcnt lgkmcnt(1)
	v_sub_f32_e32 v18, v111, v18
	v_mul_f32_e32 v18, 0x3fb8aa3b, v18
	v_exp_f32_e32 v18, v18
	s_nop 0
	v_mul_f32_e32 v18, v30, v18
	s_waitcnt lgkmcnt(0)
	v_mul_f32_e32 v18, v22, v18
	v_cndmask_b32_e32 v18, 0, v18, vcc
	v_cvt_pk_bf16_f32 v18, v18, v75
	v_add_u32_e32 v22, 0x1b980, v106
	ds_write_b16 v22, v18
	v_sub_f32_e32 v18, v111, v19
	v_mul_f32_e32 v18, 0x3fb8aa3b, v18
	v_exp_f32_e32 v18, v18
	v_cmp_lt_i32_e32 vcc, v26, v110
	v_add_u32_e32 v19, 0x1ba90, v106
	v_mul_f32_e32 v18, v31, v18
	v_mul_f32_e32 v18, v23, v18
	v_cndmask_b32_e32 v18, 0, v18, vcc
	v_cvt_pk_bf16_f32 v18, v18, v75
	ds_write_b16 v19, v18
	v_sub_f32_e32 v19, v111, v20
	v_mul_f32_e32 v19, 0x3fb8aa3b, v19
	v_exp_f32_e32 v19, v19
	v_add_u32_e32 v18, -1, v112
	v_cmp_le_i32_e32 vcc, v18, v110
	v_mul_f32_e32 v19, v32, v19
	v_mul_f32_e32 v19, v24, v19
	v_cndmask_b32_e32 v18, 0, v19, vcc
	v_cvt_pk_bf16_f32 v18, v18, v75
	v_add_u32_e32 v19, 0x1bba0, v106
	ds_write_b16 v19, v18
	v_sub_f32_e32 v18, v111, v21
	v_mul_f32_e32 v18, 0x3fb8aa3b, v18
	v_exp_f32_e32 v18, v18
	v_cmp_le_i32_e32 vcc, v112, v110
	v_add_u32_e32 v19, 0x1bcb0, v106
	v_mul_f32_e32 v18, v33, v18
	v_mul_f32_e32 v18, v25, v18
	v_cndmask_b32_e32 v18, 0, v18, vcc
	v_cvt_pk_bf16_f32 v18, v18, v75
	ds_write_b16 v19, v18
	s_cbranch_scc0 .LBB0_2435
	v_mov_b32_e32 v20, v81
	v_mov_b32_e32 v19, v96
.LBB0_2437:
	v_add_u32_e32 v18, s5, v20
	v_mul_lo_u32 v18, v18, s53
	v_add3_u32 v18, s33, v19, v18
	v_cvt_pk_bf16_f32 v20, v2, v75
	ds_write_b16 v18, v20
	v_cvt_pk_bf16_f32 v19, v3, v75
	ds_write_b16 v18, v19 offset:144
	v_cvt_pk_bf16_f32 v19, v4, v75
	ds_write_b16 v18, v19 offset:288
	v_cvt_pk_bf16_f32 v19, v5, v75
	ds_write_b16 v18, v19 offset:432
	v_cvt_pk_bf16_f32 v19, v6, v75
	ds_write_b16 v18, v19 offset:1152
	v_cvt_pk_bf16_f32 v19, v7, v75
	ds_write_b16 v18, v19 offset:1296
	v_cvt_pk_bf16_f32 v19, v8, v75
	ds_write_b16 v18, v19 offset:1440
	v_cvt_pk_bf16_f32 v19, v9, v75
	ds_write_b16 v18, v19 offset:1584
	v_cvt_pk_bf16_f32 v19, v10, v75
	ds_write_b16 v18, v19 offset:2304
	v_cvt_pk_bf16_f32 v19, v11, v75
	ds_write_b16 v18, v19 offset:2448
	v_cvt_pk_bf16_f32 v19, v12, v75
	ds_write_b16 v18, v19 offset:2592
	v_cvt_pk_bf16_f32 v19, v13, v75
	ds_write_b16 v18, v19 offset:2736
	v_cvt_pk_bf16_f32 v19, v14, v75
	ds_write_b16 v18, v19 offset:3456
	v_cvt_pk_bf16_f32 v19, v15, v75
	ds_write_b16 v18, v19 offset:3600
	v_cvt_pk_bf16_f32 v19, v16, v75
	ds_write_b16 v18, v19 offset:3744
	v_cvt_pk_bf16_f32 v19, v17, v75
	ds_write_b16 v18, v19 offset:3888
	v_mov_b32_e32 v18, v87
	s_waitcnt lgkmcnt(0)
	s_barrier
	s_add_i32 s38, 0, 0x22800
	v_and_b32_e32 v101, 31, v18
	v_ashrrev_i32_e32 v100, 5, v18
	v_ashrrev_i32_e32 v105, 2, v18
	v_bfe_u32 v102, v18, 2, 2
	v_and_b32_e32 v103, 16, v18
	v_lshlrev_b32_e32 v18, 2, v18
	v_and_b32_e32 v104, 12, v18
	v_or_b32_e32 v98, v104, v103
	v_or_b32_e32 v18, s40, v98
	v_and_or_b32 v74, v105, -8, v102
	v_lshlrev_b32_e32 v97, 1, v18
	v_add_u32_e32 v118, s38, v97
	v_mul_lo_u32 v96, v74, s53
	v_add_u32_e32 v18, v118, v96
	v_add3_u32 v20, s38, v96, v97
	ds_read_b64_tr_b16 v[120:121], v18
	ds_read_b64_tr_b16 v[122:123], v20 offset:576
	v_or_b32_e32 v99, s5, v101
	v_mul_lo_u32 v22, v99, s55
	v_lshlrev_b32_e32 v23, 4, v100
	v_add3_u32 v119, s54, v22, v23
	ds_read_b128 v[124:127], v119
	v_add_u32_e32 v81, 0x900, v96
	v_add_u32_e32 v106, v118, v81
	ds_read_b64_tr_b16 v[128:129], v106
	v_add3_u32 v81, s38, v81, v97
	ds_read_b64_tr_b16 v[130:131], v81 offset:576
	ds_read_b128 v[132:135], v119 offset:32
	v_add_u32_e32 v81, 0x1200, v96
	v_add_u32_e32 v106, v118, v81
	ds_read_b64_tr_b16 v[136:137], v106
	v_add3_u32 v81, s38, v81, v97
	ds_read_b64_tr_b16 v[138:139], v81 offset:576
	ds_read_b128 v[140:143], v119 offset:64
	ds_read_b128 v[148:151], v119 offset:96
	v_add_u32_e32 v81, 0x1b00, v96
	v_add_u32_e32 v106, v118, v81
	v_add3_u32 v81, s38, v81, v97
	ds_read_b64_tr_b16 v[144:145], v106
	ds_read_b64_tr_b16 v[146:147], v81 offset:576
	s_waitcnt lgkmcnt(9)
	v_mfma_f32_32x32x16_bf16 v[18:33], v[120:123], v[124:127], 0
	v_add_u32_e32 v81, 0x2400, v96
	v_add_u32_e32 v106, v118, v81
	ds_read_b64_tr_b16 v[152:153], v106
	v_add3_u32 v81, s38, v81, v97
	ds_read_b64_tr_b16 v[154:155], v81 offset:576
	ds_read_b128 v[156:159], v119 offset:128
	s_waitcnt lgkmcnt(9)
	v_mfma_f32_32x32x16_bf16 v[18:33], v[128:131], v[132:135], v[18:33]
	ds_read_b128 v[124:127], v119 offset:160
	v_add_u32_e32 v81, 0x2d00, v96
	v_add_u32_e32 v106, v118, v81
	v_add3_u32 v108, s38, v81, v97
	ds_read_b64_tr_b16 v[120:121], v106
	ds_read_b64_tr_b16 v[122:123], v108 offset:576
	s_waitcnt lgkmcnt(9)
	v_mfma_f32_32x32x16_bf16 v[18:33], v[136:139], v[140:143], v[18:33]
	v_add_u32_e32 v108, 0x3600, v96
	v_add_u32_e32 v106, v118, v108
	ds_read_b64_tr_b16 v[128:129], v106
	v_add3_u32 v108, s38, v108, v97
	ds_read_b64_tr_b16 v[130:131], v108 offset:576
	ds_read_b128 v[132:135], v119 offset:192
	s_waitcnt lgkmcnt(9)
	v_mfma_f32_32x32x16_bf16 v[18:33], v[144:147], v[148:151], v[18:33]
	v_add_u32_e32 v114, 0x3f00, v96
	v_add_u32_e32 v115, v118, v114
	v_add3_u32 v116, s38, v114, v97
	ds_read_b64_tr_b16 v[136:137], v115
	ds_read_b64_tr_b16 v[138:139], v116 offset:576
	ds_read_b128 v[140:143], v119 offset:224
	s_waitcnt lgkmcnt(9)
	v_mfma_f32_32x32x16_bf16 v[18:33], v[152:155], v[156:159], v[18:33]
	s_waitcnt lgkmcnt(6)
	v_mfma_f32_32x32x16_bf16 v[18:33], v[120:123], v[124:127], v[18:33]
	s_waitcnt lgkmcnt(3)
	v_mfma_f32_32x32x16_bf16 v[18:33], v[128:131], v[132:135], v[18:33]
	s_waitcnt lgkmcnt(0)
	v_mfma_f32_32x32x16_bf16 v[18:33], v[136:139], v[140:143], v[18:33]
	v_lshl_add_u32 v106, v99, 2, 0
	v_add_u32_e32 v106, 0x27000, v106
	ds_read_b32 v107, v106
	s_mov_b64 s[38:39], -1
	s_and_b64 vcc, exec, s[2:3]
	v_or_b32_e32 v106, s5, v98
	s_cbranch_vccz .LBB0_2439
	v_lshlrev_b32_e32 v98, 1, v106
	s_mov_b64 s[38:39], 0
